# ssd_pass1: dt / bias / A_log loads of the cumulative-sum stage issued before the entry barrier instead of two serial round trips after it
# baseline (speedup 1.0000x reference)
; #define LAS __attribute__((address_space(3)))
; DI float bperm(float v, int srclane) { return __int_as_float(__builtin_amdgcn_ds_bpermute(srclane << 2, __float_as_int(v))); }
; DI float softplus_f(float x) { return x > 20.f ? x : log1pf(__expf(x)); }
; DI void ssd_acs(const float* DT, const LayerP& P, int row0, int h, LAS float* acs, LAS float* dtl, int lane) {
;     const float bias = P.ssd_dtb[h], A = -__expf(P.ssd_alog[h]);
;     const float d0 = softplus_f(DT[(size_t)(row0 + 2 * lane) * 4 + h] + bias), d1 = softplus_f(DT[(size_t)(row0 + 2 * lane + 1) * 4 + h] + bias);
;     const float a0 = d0 * A, a1 = d1 * A; float incl = a0 + a1;
; #pragma unroll
;     for (int o = 1; o < 64; o <<= 1) { const float t = bperm(incl, lane - o); if (lane >= o) incl += t; }
;     const float excl = incl - (a0 + a1);
;     acs[2 * lane] = excl + a0; acs[2 * lane + 1] = incl; dtl[2 * lane] = d0; dtl[2 * lane + 1] = d1;
; }
; DI void ssd_pass1(LAS unsigned char* lds, const Args& a, const LayerP& P, int unit, int wv) {
;     ...
;     if (wave < 4) ssd_acs((const float*)(a.ws + WS_DT), P, row0, wave, acs + wave * 128, dtl + wave * 128, lane);
.LBB0_986:
	s_or_b64 exec, exec, s[2:3]
	s_cmp_lt_u32 s77, 4
	s_cbranch_scc0 .Lmy_acs1_skip
	v_and_b32_e32 v226, 63, v165
	s_lshl_b32 s32, s7, 14
	s_or_b32 s32, s32, s12
	v_lshlrev_b32_e32 v226, 1, v226
	v_or_b32_e32 v226, s32, v226
	v_ashrrev_i32_e32 v227, 31, v226
	v_lshl_add_u64 v[228:229], v[226:227], 4, s[94:95]
	global_load_dword v222, v[228:229], off
	global_load_dword v225, v[228:229], off offset:16
	global_load_dword v223, v1, s[48:49]
	global_load_dword v224, v1, s[50:51]
.Lmy_acs1_skip:
	v_readlane_b32 s2, v254, 4
	v_readlane_b32 s3, v254, 5
	s_andn2_b64 vcc, exec, s[2:3]
	s_barrier
	s_cbranch_vccnz .LBB0_992
	v_and_b32_e32 v119, 63, v165
	s_lshl_b32 s2, s7, 14
	s_or_b32 s2, s2, s12
	v_lshlrev_b32_e32 v0, 1, v119
	v_or_b32_e32 v116, s2, v0
	v_ashrrev_i32_e32 v117, 31, v116
	v_lshl_add_u64 v[114:115], v[116:117], 4, s[94:95]
	s_waitcnt vmcnt(0)
	v_mov_b32_e32 v114, v222
	s_nop 0
	v_mov_b32_e32 v115, v223
	v_mov_b32_e32 v117, v224
	s_mov_b32 s2, 0x41a00000
	s_nop 0
	v_add_f32_e32 v114, v115, v114
	v_cmp_nlt_f32_e32 vcc, s2, v114
	s_and_saveexec_b64 s[2:3], vcc
	s_cbranch_execz .LBB0_989
	v_mul_f32_e32 v114, 0x3fb8aa3b, v114
	v_exp_f32_e32 v114, v114
	s_nop 0
	v_add_f32_e32 v122, 1.0, v114
	v_frexp_mant_f32_e32 v124, v122
	v_cvt_f64_f32_e32 v[120:121], v122
	v_frexp_exp_i32_f64_e32 v120, v[120:121]
	v_cmp_gt_f32_e32 vcc, s75, v124
	v_add_f32_e32 v123, -1.0, v122
	v_sub_f32_e32 v125, v123, v122
	v_subbrev_co_u32_e32 v128, vcc, 0, v120, vcc
	v_sub_u32_e32 v120, 0, v128
	v_sub_f32_e32 v123, v114, v123
	v_add_f32_e32 v125, 1.0, v125
	v_ldexp_f32 v121, v122, v120
	v_add_f32_e32 v123, v123, v125
	v_add_f32_e32 v122, -1.0, v121
	v_add_f32_e32 v124, 1.0, v121
	v_ldexp_f32 v120, v123, v120
	v_add_f32_e32 v123, 1.0, v122
	v_add_f32_e32 v125, -1.0, v124
	v_sub_f32_e32 v123, v121, v123
	v_sub_f32_e32 v121, v121, v125
	v_add_f32_e32 v123, v120, v123
	v_add_f32_e32 v120, v120, v121
	v_add_f32_e32 v129, v124, v120
	v_rcp_f32_e32 v131, v129
	v_sub_f32_e32 v121, v129, v124
	v_sub_f32_e32 v130, v120, v121
	v_add_f32_e32 v121, v122, v123
	v_mul_f32_e32 v133, v121, v131
	v_sub_f32_e32 v120, v121, v122
	v_mul_f32_e32 v122, v129, v133
	v_fma_f32 v124, v133, v129, -v122
	v_fmac_f32_e32 v124, v133, v130
	v_sub_f32_e32 v132, v123, v120
	v_add_f32_e32 v120, v122, v124
	v_sub_f32_e32 v123, v121, v120
	v_pk_add_f32 v[126:127], v[120:121], v[122:123] neg_lo:[0,1] neg_hi:[0,1]
	v_mov_b32_e32 v125, v120
	v_pk_add_f32 v[120:121], v[126:127], v[124:125] neg_lo:[0,1] neg_hi:[0,1]
	v_cmp_neq_f32_e32 vcc, s84, v114
	v_add_f32_e32 v121, v132, v121
	v_add_f32_e32 v120, v120, v121
	v_add_f32_e32 v121, v123, v120
	v_mul_f32_e32 v132, v131, v121
	v_mul_f32_e32 v122, v129, v132
	v_fma_f32 v124, v132, v129, -v122
	v_fmac_f32_e32 v124, v132, v130
	v_sub_f32_e32 v123, v123, v121
	v_add_f32_e32 v129, v120, v123
	v_add_f32_e32 v120, v122, v124
	v_sub_f32_e32 v123, v121, v120
	v_pk_add_f32 v[126:127], v[120:121], v[122:123] neg_lo:[0,1] neg_hi:[0,1]
	v_mov_b32_e32 v125, v120
	v_pk_add_f32 v[120:121], v[126:127], v[124:125] neg_lo:[0,1] neg_hi:[0,1]
	s_nop 0
	v_add_f32_e32 v121, v129, v121
	v_add_f32_e32 v120, v120, v121
	v_add_f32_e32 v121, v133, v132
	v_add_f32_e32 v120, v123, v120
	v_sub_f32_e32 v122, v121, v133
	v_mul_f32_e32 v120, v131, v120
	v_sub_f32_e32 v122, v132, v122
	v_add_f32_e32 v122, v122, v120
	v_add_f32_e32 v124, v121, v122
	v_mul_f32_e32 v125, v124, v124
	v_fmamk_f32 v120, v125, 0x3e9b6dac, v203
	v_fmaak_f32 v189, v125, v120, 0x3f2aaada
	v_cvt_f32_i32_e32 v120, v128
	v_sub_f32_e32 v121, v124, v121
	v_sub_f32_e32 v121, v122, v121
	v_ldexp_f32 v126, v121, 1
	v_mul_f32_e32 v121, v124, v125
	v_ldexp_f32 v123, v124, 1
	v_pk_mul_f32 v[124:125], v[120:121], v[188:189]
	s_nop 0
	v_fma_f32 v122, v120, s31, -v124
	v_fmac_f32_e32 v122, 0xb102e308, v120
	v_pk_add_f32 v[120:121], v[124:125], v[122:123]
	s_nop 0
	v_sub_f32_e32 v123, v121, v123
	v_sub_f32_e32 v123, v125, v123
	v_add_f32_e32 v127, v126, v123
	v_mov_b32_e32 v126, v124
	v_pk_add_f32 v[124:125], v[120:121], v[124:125] neg_lo:[0,1] neg_hi:[0,1]
	v_pk_add_f32 v[128:129], v[120:121], v[126:127]
	v_mov_b32_e32 v123, v120
	v_mov_b32_e32 v125, v129
	v_pk_add_f32 v[130:131], v[122:123], v[124:125] neg_lo:[0,1] neg_hi:[0,1]
	v_pk_add_f32 v[122:123], v[122:123], v[124:125]
	v_mov_b32_e32 v126, v127
	v_pk_add_f32 v[124:125], v[122:123], v[120:121] op_sel:[1,0] op_sel_hi:[0,1] neg_lo:[0,1] neg_hi:[0,1]
	v_pk_add_f32 v[132:133], v[128:129], v[124:125] op_sel_hi:[1,0] neg_lo:[0,1] neg_hi:[0,1]
	v_mov_b32_e32 v128, v129
	v_mov_b32_e32 v129, v123
	v_pk_mov_b32 v[124:125], v[120:121], v[124:125] op_sel:[1,0]
	v_mov_b32_e32 v127, v120
	v_pk_add_f32 v[124:125], v[128:129], v[124:125] neg_lo:[0,1] neg_hi:[0,1]
	v_mov_b32_e32 v132, v130
	v_pk_add_f32 v[120:121], v[126:127], v[124:125] neg_lo:[0,1] neg_hi:[0,1]
	v_mov_b32_e32 v131, v123
	v_pk_add_f32 v[124:125], v[132:133], v[120:121]
	s_nop 0
	v_pk_add_f32 v[126:127], v[124:125], v[124:125] op_sel:[0,1] op_sel_hi:[1,0]
	s_nop 0
	v_pk_add_f32 v[122:123], v[122:123], v[126:127] op_sel:[1,0] op_sel_hi:[0,1]
	v_mov_b32_e32 v125, v122
	v_pk_add_f32 v[128:129], v[124:125], v[130:131] neg_lo:[0,1] neg_hi:[0,1]
	v_mov_b32_e32 v121, v126
	v_sub_f32_e32 v123, v124, v128
	v_pk_add_f32 v[120:121], v[120:121], v[128:129] neg_lo:[0,1] neg_hi:[0,1]
	v_sub_f32_e32 v123, v130, v123
	v_add_f32_e32 v120, v120, v123
	v_add_f32_e32 v120, v120, v121
	v_add_f32_e32 v120, v122, v120
	v_cndmask_b32_e32 v120, v206, v120, vcc
	v_cmp_ngt_f32_e32 vcc, -1.0, v114
	s_nop 1
	v_cndmask_b32_e32 v120, v207, v120, vcc
	v_cmp_neq_f32_e32 vcc, -1.0, v114
	s_nop 1
	v_cndmask_b32_e32 v120, v208, v120, vcc
	v_cmp_lt_f32_e64 vcc, |v114|, s85
	s_nop 1
	v_cndmask_b32_e32 v114, v120, v114, vcc
; DI float softplus_f(float x) { return x > 20.f ? x : log1pf(__expf(x)); }
; DI void ssd_acs(const float* DT, const LayerP& P, int row0, int h, LAS float* acs, LAS float* dtl, int lane) {
;     ...
;     const float d0 = softplus_f(DT[(size_t)(row0 + 2 * lane) * 4 + h] + bias), d1 = softplus_f(DT[(size_t)(row0 + 2 * lane + 1) * 4 + h] + bias);
.LBB0_989:
	s_or_b64 exec, exec, s[2:3]
	v_or_b32_e32 v120, 1, v116
	v_ashrrev_i32_e32 v121, 31, v120
	v_lshl_add_u64 v[120:121], v[120:121], 4, s[94:95]
	v_mov_b32_e32 v116, v225
	s_mov_b32 s2, 0x41a00000
	s_nop 0
	v_add_f32_e32 v115, v115, v116
	v_cmp_nlt_f32_e32 vcc, s2, v115
	s_and_saveexec_b64 s[2:3], vcc
	s_cbranch_execz .LBB0_991
	v_mul_f32_e32 v115, 0x3fb8aa3b, v115
	v_exp_f32_e32 v115, v115
	s_nop 0
	v_add_f32_e32 v116, 1.0, v115
	v_frexp_mant_f32_e32 v123, v116
	v_cvt_f64_f32_e32 v[120:121], v116
	v_add_f32_e32 v122, -1.0, v116
	v_frexp_exp_i32_f64_e32 v120, v[120:121]
	v_cmp_gt_f32_e32 vcc, s75, v123
	v_sub_f32_e32 v124, v122, v116
	v_sub_f32_e32 v122, v115, v122
	v_subbrev_co_u32_e32 v128, vcc, 0, v120, vcc
	v_add_f32_e32 v124, 1.0, v124
	v_sub_u32_e32 v120, 0, v128
	v_add_f32_e32 v122, v122, v124
	v_ldexp_f32 v116, v116, v120
	v_ldexp_f32 v120, v122, v120
	v_add_f32_e32 v122, -1.0, v116
	v_add_f32_e32 v121, 1.0, v122
	v_sub_f32_e32 v121, v116, v121
	v_add_f32_e32 v123, v120, v121
	v_add_f32_e32 v121, 1.0, v116
	v_add_f32_e32 v124, -1.0, v121
	v_sub_f32_e32 v116, v116, v124
	v_add_f32_e32 v116, v120, v116
	v_add_f32_e32 v129, v121, v116
	v_rcp_f32_e32 v130, v129
	v_sub_f32_e32 v120, v129, v121
	v_add_f32_e32 v121, v122, v123
	v_sub_f32_e32 v116, v116, v120
	v_mul_f32_e32 v132, v121, v130
	v_sub_f32_e32 v120, v121, v122
	v_mul_f32_e32 v122, v129, v132
	v_fma_f32 v124, v132, v129, -v122
	v_fmac_f32_e32 v124, v132, v116
	v_sub_f32_e32 v131, v123, v120
	v_add_f32_e32 v120, v122, v124
	v_sub_f32_e32 v123, v121, v120
	v_pk_add_f32 v[126:127], v[120:121], v[122:123] neg_lo:[0,1] neg_hi:[0,1]
	v_mov_b32_e32 v125, v120
	v_pk_add_f32 v[120:121], v[126:127], v[124:125] neg_lo:[0,1] neg_hi:[0,1]
	v_cmp_neq_f32_e32 vcc, s84, v115
	v_add_f32_e32 v121, v131, v121
	v_add_f32_e32 v120, v120, v121
	v_add_f32_e32 v121, v123, v120
	v_mul_f32_e32 v131, v130, v121
	v_mul_f32_e32 v122, v129, v131
	v_fma_f32 v124, v131, v129, -v122
	v_fmac_f32_e32 v124, v131, v116
	v_sub_f32_e32 v116, v123, v121
	v_add_f32_e32 v116, v120, v116
	v_add_f32_e32 v120, v122, v124
	v_sub_f32_e32 v123, v121, v120
	v_pk_add_f32 v[126:127], v[120:121], v[122:123] neg_lo:[0,1] neg_hi:[0,1]
	v_mov_b32_e32 v125, v120
	v_pk_add_f32 v[120:121], v[126:127], v[124:125] neg_lo:[0,1] neg_hi:[0,1]
	s_nop 0
	v_add_f32_e32 v116, v116, v121
	v_add_f32_e32 v116, v120, v116
	v_add_f32_e32 v121, v132, v131
	v_add_f32_e32 v116, v123, v116
	v_sub_f32_e32 v120, v121, v132
	v_mul_f32_e32 v116, v130, v116
	v_sub_f32_e32 v120, v131, v120
	v_add_f32_e32 v116, v120, v116
	v_add_f32_e32 v122, v121, v116
	v_mul_f32_e32 v124, v122, v122
	v_fmamk_f32 v120, v124, 0x3e9b6dac, v203
	v_fmaak_f32 v189, v124, v120, 0x3f2aaada
	v_cvt_f32_i32_e32 v120, v128
	v_sub_f32_e32 v121, v122, v121
	v_sub_f32_e32 v116, v116, v121
	v_mul_f32_e32 v121, v122, v124
	v_pk_mul_f32 v[124:125], v[120:121], v[188:189]
	v_ldexp_f32 v123, v122, 1
	v_fma_f32 v122, v120, s31, -v124
	v_fmac_f32_e32 v122, 0xb102e308, v120
	v_pk_add_f32 v[120:121], v[124:125], v[122:123]
	v_ldexp_f32 v116, v116, 1
	v_sub_f32_e32 v123, v121, v123
	v_sub_f32_e32 v123, v125, v123
	v_add_f32_e32 v127, v116, v123
	v_mov_b32_e32 v126, v124
	v_pk_add_f32 v[124:125], v[120:121], v[124:125] neg_lo:[0,1] neg_hi:[0,1]
	v_pk_add_f32 v[128:129], v[120:121], v[126:127]
	v_mov_b32_e32 v123, v120
	v_mov_b32_e32 v125, v129
	v_pk_add_f32 v[130:131], v[122:123], v[124:125] neg_lo:[0,1] neg_hi:[0,1]
	v_pk_add_f32 v[122:123], v[122:123], v[124:125]
	v_mov_b32_e32 v126, v127
	v_pk_add_f32 v[124:125], v[122:123], v[120:121] op_sel:[1,0] op_sel_hi:[0,1] neg_lo:[0,1] neg_hi:[0,1]
	v_pk_add_f32 v[132:133], v[128:129], v[124:125] op_sel_hi:[1,0] neg_lo:[0,1] neg_hi:[0,1]
	v_mov_b32_e32 v128, v129
	v_mov_b32_e32 v129, v123
	v_pk_mov_b32 v[124:125], v[120:121], v[124:125] op_sel:[1,0]
	v_mov_b32_e32 v127, v120
	v_pk_add_f32 v[124:125], v[128:129], v[124:125] neg_lo:[0,1] neg_hi:[0,1]
	v_mov_b32_e32 v132, v130
	v_pk_add_f32 v[120:121], v[126:127], v[124:125] neg_lo:[0,1] neg_hi:[0,1]
	v_mov_b32_e32 v131, v123
	v_pk_add_f32 v[124:125], v[132:133], v[120:121]
	s_nop 0
	v_pk_add_f32 v[126:127], v[124:125], v[124:125] op_sel:[0,1] op_sel_hi:[1,0]
	s_nop 0
	v_pk_add_f32 v[122:123], v[122:123], v[126:127] op_sel:[1,0] op_sel_hi:[0,1]
	v_mov_b32_e32 v125, v122
	v_pk_add_f32 v[128:129], v[124:125], v[130:131] neg_lo:[0,1] neg_hi:[0,1]
	v_mov_b32_e32 v121, v126
	v_sub_f32_e32 v116, v124, v128
	v_pk_add_f32 v[120:121], v[120:121], v[128:129] neg_lo:[0,1] neg_hi:[0,1]
	v_sub_f32_e32 v116, v130, v116
	v_add_f32_e32 v116, v120, v116
	v_add_f32_e32 v116, v116, v121
	v_add_f32_e32 v116, v122, v116
	v_cndmask_b32_e32 v116, v206, v116, vcc
	v_cmp_ngt_f32_e32 vcc, -1.0, v115
	s_nop 1
	v_cndmask_b32_e32 v116, v207, v116, vcc
	v_cmp_neq_f32_e32 vcc, -1.0, v115
	s_nop 1
	v_cndmask_b32_e32 v116, v208, v116, vcc
	v_cmp_lt_f32_e64 vcc, |v115|, s85
	s_nop 1
	v_cndmask_b32_e32 v115, v116, v115, vcc
